# placement: FFN-F2 loop head moved to the same 64-byte phase as the F1G and F3 loop heads
# baseline (speedup 1.0000x reference)
.LBB0_1051:
	v_lshrrev_b32_e32 v15, 1, v14
	v_and_b32_e32 v15, 24, v15
	v_and_b32_e32 v221, 15, v14
	v_lshlrev_b32_e32 v16, 1, v15
	v_lshlrev_b32_e32 v14, 2, v14
	s_lshl_b32 s3, s3, 5
	s_lshl_b32 s60, s4, 6
	v_lshl_or_b32 v16, v221, 6, v16
	s_lshl_b32 s4, s4, 13
	v_and_b32_e32 v14, 32, v14
	s_and_b32 s3, s3, 0x60
	s_add_i32 m0, s42, 0x18000
	v_lshl_add_u64 v[6:7], v[6:7], 0, s[74:75]
	v_bitop3_b32 v17, v16, s4, v14 bitop3:0xde
	s_lshl_b32 s4, s3, 7
	s_waitcnt vmcnt(2)
	s_barrier
	global_load_lds_dwordx4 v[6:7], off
	v_lshl_add_u64 v[4:5], v[4:5], 0, s[74:75]
	s_add_i32 m0, s42, 0x1a000
	s_add_i32 s61, s42, 0x8000
	s_add_i32 s64, s42, 0xa000
	v_bitop3_b32 v222, v16, s4, v14 bitop3:0xde
	global_load_lds_dwordx4 v[4:5], off
	v_lshl_add_u64 v[0:1], v[0:1], 0, s[74:75]
	s_mov_b32 m0, s61
	s_add_u32 s4, s12, 0x80080
	global_load_lds_dwordx4 v[0:1], off
	v_lshl_add_u64 v[0:1], v[2:3], 0, s[74:75]
	s_mov_b32 m0, s64
	s_addc_u32 s5, s13, 0
	global_load_lds_dwordx4 v[0:1], off
	s_add_i32 m0, s42, 0x1c000
	v_lshl_add_u64 v[0:1], s[4:5], 0, v[176:177]
	global_load_lds_dwordx4 v[0:1], off
	v_lshl_add_u64 v[0:1], s[4:5], 0, v[178:179]
	s_add_i32 m0, s42, 0x1e000
	s_cmpk_lt_u32 s2, 0x100
	global_load_lds_dwordx4 v[0:1], off
	v_lshlrev_b32_e32 v0, 15, v12
	v_and_b32_e32 v0, 0xffff0000, v0
	v_lshl_add_u32 v0, v11, 12, v0
	v_and_b32_e32 v1, 1, v12
	v_lshl_or_b32 v0, v1, 6, v0
	v_lshl_add_u32 v184, v13, 1, v0
	v_lshlrev_b32_e32 v0, 15, v8
	s_cselect_b64 s[40:41], -1, 0
	s_add_u32 s46, s18, 0x5800
	v_and_b32_e32 v0, 0xffff0000, v0
	s_waitcnt vmcnt(6)
	s_addc_u32 s47, s19, 0
	v_lshl_add_u32 v0, v9, 12, v0
	v_and_b32_e32 v1, 1, v8
	s_add_u32 s48, s18, 0xb000
	v_lshl_or_b32 v0, v1, 6, v0
	v_readlane_b32 s14, v254, 39
	s_mov_b32 s65, 0
	v_cmp_eq_u32_e64 s[4:5], 0, v221
	v_cmp_eq_u32_e64 s[6:7], 15, v221
	s_addc_u32 s49, s19, 0
	v_or_b32_e32 v223, s3, v15
	v_mov_b32_e32 v185, v177
	v_lshl_add_u32 v186, v10, 1, v0
	v_mov_b32_e32 v187, v177
	v_add_u32_e32 v224, 0, v17
	v_readlane_b32 s2, v254, 38
	s_mov_b32 s3, s14
	s_barrier
	v_readlane_b32 s15, v254, 40
	s_branch .LBB0_1054
	s_nop 0
	s_nop 0
	s_nop 0
	s_nop 0

.LBB0_1154:
	s_lshl_b32 s6, s20, 1
	s_or_b32 s13, s6, 1
	s_mul_i32 s7, s13, 0x3000
	s_mul_hi_u32 s6, s13, 0x3000
	s_add_u32 s7, s18, s7
	s_addc_u32 s6, s19, s6
	s_add_u32 s42, s7, 0x20000
	s_addc_u32 s43, s6, 0
	s_lshl_b32 s72, s20, 11
	s_lshl_b64 s[6:7], s[72:73], 2
	s_waitcnt lgkmcnt(0)
	s_add_u32 s36, s4, s6
	s_addc_u32 s37, s5, s7
	s_add_u32 s14, s18, 0x40000
	s_mul_i32 s4, s20, 0xc000
	s_addc_u32 s15, s19, 0
	s_add_i32 s6, s4, 0xc000
	s_and_b64 s[4:5], exec, s[8:9]
	s_cselect_b32 s72, 0, s6
	s_lshl_b64 s[4:5], s[72:73], 2
	s_add_u32 s6, s14, s4
	s_addc_u32 s7, s15, s5
	s_mul_hi_u32 s4, s13, 0x18000
	s_mul_i32 s13, s13, 0x18000
	s_add_u32 s40, s14, s13
	s_addc_u32 s41, s15, s4
	s_add_u32 s46, s18, 0x100000
	s_addc_u32 s47, s19, 0
	s_add_u32 s48, s18, 0x10200
	s_addc_u32 s49, s19, 0
	s_and_b32 s8, s3, 3
	s_lshl_b32 s3, s12, 6
	s_lshl_b32 s9, s12, 13
	s_lshl_b32 s13, s8, 12
	s_add_u32 s18, s18, 0x8800000
	s_addc_u32 s19, s19, 0
	s_add_i32 m0, s28, 0x18000
	v_lshl_add_u64 v[6:7], v[6:7], 0, s[74:75]
	s_waitcnt vmcnt(2)
	s_barrier
	global_load_lds_dwordx4 v[6:7], off
	v_lshl_add_u64 v[4:5], v[4:5], 0, s[74:75]
	s_add_i32 m0, s28, 0x1a000
	s_add_i32 s44, s28, 0x8000
	s_add_i32 s45, s28, 0xa000
	global_load_lds_dwordx4 v[4:5], off
	v_lshl_add_u64 v[0:1], v[0:1], 0, s[74:75]
	s_mov_b32 m0, s44
	s_add_u32 s4, s30, 0x160080
	global_load_lds_dwordx4 v[0:1], off
	v_lshl_add_u64 v[0:1], v[2:3], 0, s[74:75]
	s_mov_b32 m0, s45
	s_addc_u32 s5, s31, 0
	global_load_lds_dwordx4 v[0:1], off
	s_add_i32 m0, s28, 0x1c000
	v_lshl_add_u64 v[0:1], s[4:5], 0, v[176:177]
	global_load_lds_dwordx4 v[0:1], off
	v_lshl_add_u64 v[0:1], s[4:5], 0, v[182:183]
	s_add_i32 m0, s28, 0x1e000
	v_lshlrev_b32_e32 v5, 2, v15
	global_load_lds_dwordx4 v[0:1], off
	v_and_b32_e32 v0, 15, v15
	v_bfe_u32 v1, v15, 4, 2
	v_or_b32_e32 v184, s3, v0
	v_lshlrev_b32_e32 v2, 4, v1
	v_lshlrev_b32_e32 v3, 2, v184
	s_cmpk_lt_u32 s2, 0x100
	v_lshl_or_b32 v2, v0, 6, v2
	v_and_b32_e32 v4, 32, v3
	v_and_b32_e32 v5, 32, v5
	s_cselect_b64 s[52:53], -1, 0
	s_add_i32 s2, s3, 0x80
	v_bitop3_b32 v4, v2, s9, v4 bitop3:0xde
	v_bitop3_b32 v204, v2, s13, v5 bitop3:0xde
	v_lshlrev_b32_e32 v2, 4, v0
	v_ashrrev_i32_e32 v185, 31, v184
	v_or_b32_e32 v0, s2, v0
	s_ashr_i32 s2, s3, 31
	v_lshl_add_u64 v[186:187], v[184:185], 2, s[6:7]
	v_mov_b32_e32 v185, s2
	v_lshl_add_u64 v[188:189], v[184:185], 2, s[6:7]
	s_mov_b64 s[2:3], 0xc0
	v_lshl_add_u64 v[194:195], v[188:189], 0, s[2:3]
	s_lshl_b32 s2, s8, 2
	s_lshl_b32 s9, s12, 10
	s_add_i32 s2, s2, 0
	s_add_i32 s2, s2, s9
	s_add_i32 s6, s2, 0x20c00
	v_readlane_b32 s2, v254, 57
	s_movk_i32 s7, 0x1600
	v_lshlrev_b32_e32 v6, 3, v1
	v_cmp_eq_u32_e64 s[4:5], 0, v1
	v_lshl_add_u32 v209, v0, 2, s2
	v_lshrrev_b32_e32 v1, 1, v8
	v_mul_lo_u32 v0, v9, s7
	v_add_u32_e32 v185, s2, v3
	v_mad_u64_u32 v[0:1], s[2:3], v1, s97, v[0:1]
	v_or_b32_e32 v0, v0, v10
	v_lshl_or_b32 v205, s8, 5, v6
	v_add_lshl_u32 v0, v0, v11, 1
	v_mov_b32_e32 v1, v177
	s_mov_b64 s[8:9], 0x160080
	v_lshl_add_u64 v[196:197], v[0:1], 0, s[8:9]
	v_lshrrev_b32_e32 v1, 1, v12
	v_mul_lo_u32 v0, v13, s7
	v_mad_u64_u32 v[0:1], s[2:3], v1, s97, v[0:1]
	s_waitcnt vmcnt(6)
	s_cmp_eq_u64 s[16:17], 0
	v_or_b32_e32 v0, v0, v14
	s_cselect_b64 s[54:55], -1, 0
	s_cmp_lg_u64 s[16:17], 0
	v_add_lshl_u32 v0, v0, v16, 1
	v_mov_b32_e32 v1, v177
	s_mov_b32 s58, 0
	v_lshl_add_u64 v[190:191], v[188:189], 0, 64
	v_lshl_add_u64 v[192:193], v[188:189], 0, s[74:75]
	s_cselect_b64 s[56:57], -1, 0
	v_add_u32_e32 v206, 64, v185
	v_add_u32_e32 v207, 0x80, v185
	v_add_u32_e32 v208, 0xc0, v185
	v_add_u32_e32 v220, 64, v209
	v_add_u32_e32 v221, 0x80, v209
	v_add_u32_e32 v222, 0xc0, v209
	v_lshl_add_u64 v[198:199], v[0:1], 0, s[8:9]
	v_add_u32_e32 v223, 0, v4
	v_add_u32_e32 v224, s6, v2
	s_mov_b32 s60, s94
	s_mov_b32 s62, s90
	s_mov_b64 s[68:69], s[0:1]
	s_barrier
	s_branch .LBB0_1157
	s_nop 0
	s_nop 0
	s_nop 0
	s_nop 0
	s_nop 0
	s_nop 0
	s_nop 0
	s_nop 0
	s_nop 0
	s_nop 0
	s_nop 0
	s_nop 0
